# v2 + one-barrier stagger of waves 4-7 around the MLA fast128 loop (halves alternate staging/compute)
# speedup vs baseline: 1.0312x; 1.0061x over previous
.LBB0_1457:
	s_or_saveexec_b64 s[34:35], s[14:15]
	v_mov_b32_e32 v100, 0
	v_mov_b32_e32 v104, 0
	s_xor_b64 exec, exec, s[34:35]
	s_cbranch_execz .LBB0_1505
	s_and_saveexec_b64 s[6:7], vcc
	s_xor_b64 s[6:7], exec, s[6:7]
	v_lshlrev_b64 v[24:25], 12, v[24:25]
	v_lshl_add_u64 v[24:25], s[82:83], 0, v[24:25]
	v_lshl_add_u64 v[24:25], v[118:119], 1, v[24:25]
	v_lshl_add_u64 v[26:27], v[24:25], 0, s[70:71]
	s_andn2_saveexec_b64 s[6:7], s[6:7]
	v_lshlrev_b64 v[24:25], 10, v[24:25]
	v_lshl_add_u64 v[24:25], v[144:145], 0, v[24:25]
	v_lshl_add_u64 v[26:27], v[118:119], 1, v[24:25]
	s_or_b64 exec, exec, s[6:7]
	global_load_dwordx4 v[24:27], v[26:27], off
	v_or_b32_e32 v30, v52, v209
	v_cmp_gt_i32_e64 s[6:7], 8, v28
	v_cmp_lt_i32_e32 vcc, 7, v28
	v_ashrrev_i32_e32 v31, 31, v30
	s_and_saveexec_b64 s[8:9], vcc
	s_xor_b64 s[8:9], exec, s[8:9]
	v_lshlrev_b64 v[28:29], 12, v[30:31]
	v_lshl_add_u64 v[28:29], s[82:83], 0, v[28:29]
	v_lshl_add_u64 v[28:29], v[120:121], 1, v[28:29]
	v_lshl_add_u64 v[28:29], v[28:29], 0, s[70:71]
	s_andn2_saveexec_b64 s[8:9], s[8:9]
	v_lshlrev_b64 v[28:29], 10, v[30:31]
	v_lshl_add_u64 v[28:29], v[144:145], 0, v[28:29]
	v_lshl_add_u64 v[28:29], v[120:121], 1, v[28:29]
	s_or_b64 exec, exec, s[8:9]
	global_load_dwordx4 v[28:31], v[28:29], off
	v_or_b32_e32 v34, v52, v210
	v_cmp_gt_i32_e64 s[8:9], 8, v32
	v_cmp_lt_i32_e32 vcc, 7, v32
	v_ashrrev_i32_e32 v35, 31, v34
	s_and_saveexec_b64 s[10:11], vcc
	s_xor_b64 s[10:11], exec, s[10:11]
	v_lshlrev_b64 v[32:33], 12, v[34:35]
	v_lshl_add_u64 v[32:33], s[82:83], 0, v[32:33]
	v_lshl_add_u64 v[32:33], v[122:123], 1, v[32:33]
	v_lshl_add_u64 v[32:33], v[32:33], 0, s[70:71]
	s_andn2_saveexec_b64 s[10:11], s[10:11]
	v_lshlrev_b64 v[32:33], 10, v[34:35]
	v_lshl_add_u64 v[32:33], v[144:145], 0, v[32:33]
	v_lshl_add_u64 v[32:33], v[122:123], 1, v[32:33]
	s_or_b64 exec, exec, s[10:11]
	global_load_dwordx4 v[32:35], v[32:33], off
	v_or_b32_e32 v38, v52, v149
	v_cmp_gt_i32_e64 s[10:11], 8, v36
	v_cmp_lt_i32_e32 vcc, 7, v36
	v_ashrrev_i32_e32 v39, 31, v38
	s_and_saveexec_b64 s[12:13], vcc
	s_xor_b64 s[12:13], exec, s[12:13]
	v_lshlrev_b64 v[36:37], 12, v[38:39]
	v_lshl_add_u64 v[36:37], s[82:83], 0, v[36:37]
	v_lshl_add_u64 v[36:37], v[44:45], 1, v[36:37]
	v_lshl_add_u64 v[36:37], v[36:37], 0, s[70:71]
	s_andn2_saveexec_b64 s[12:13], s[12:13]
	v_lshlrev_b64 v[36:37], 10, v[38:39]
	v_lshl_add_u64 v[36:37], v[144:145], 0, v[36:37]
	v_lshl_add_u64 v[36:37], v[44:45], 1, v[36:37]
	s_or_b64 exec, exec, s[12:13]
	global_load_dwordx4 v[36:39], v[36:37], off
	v_cmp_gt_i32_e64 s[12:13], 8, v42
	v_cmp_lt_i32_e32 vcc, 7, v42
	v_or_b32_e32 v42, v52, v152
	v_ashrrev_i32_e32 v43, 31, v42
	s_and_saveexec_b64 s[14:15], vcc
	s_xor_b64 s[14:15], exec, s[14:15]
	v_lshlrev_b64 v[40:41], 12, v[42:43]
	v_lshl_add_u64 v[40:41], s[82:83], 0, v[40:41]
	v_lshl_add_u64 v[40:41], v[46:47], 1, v[40:41]
	v_lshl_add_u64 v[40:41], v[40:41], 0, s[70:71]
	s_andn2_saveexec_b64 s[14:15], s[14:15]
	v_lshlrev_b64 v[40:41], 10, v[42:43]
	v_lshl_add_u64 v[40:41], v[144:145], 0, v[40:41]
	v_lshl_add_u64 v[40:41], v[46:47], 1, v[40:41]
	s_or_b64 exec, exec, s[14:15]
	global_load_dwordx4 v[40:43], v[40:41], off
	v_or_b32_e32 v50, v52, v153
	v_cmp_gt_i32_e64 s[14:15], 8, v48
	v_cmp_lt_i32_e32 vcc, 7, v48
	v_ashrrev_i32_e32 v51, 31, v50
	s_and_saveexec_b64 s[16:17], vcc
	s_xor_b64 s[16:17], exec, s[16:17]
	v_lshlrev_b64 v[48:49], 12, v[50:51]
	v_lshl_add_u64 v[48:49], s[82:83], 0, v[48:49]
	v_lshl_add_u64 v[48:49], v[102:103], 1, v[48:49]
	v_lshl_add_u64 v[48:49], v[48:49], 0, s[70:71]
	s_andn2_saveexec_b64 s[16:17], s[16:17]
	v_lshlrev_b64 v[48:49], 10, v[50:51]
	v_lshl_add_u64 v[48:49], v[144:145], 0, v[48:49]
	v_lshl_add_u64 v[48:49], v[102:103], 1, v[48:49]
	s_or_b64 exec, exec, s[16:17]
	v_and_b32_e32 v155, 0x7e, v105
	v_or_b32_e32 v54, v155, v52
	v_or_b32_e32 v52, 1, v54
	v_ashrrev_i32_e32 v55, 31, v54
	v_lshlrev_b32_e32 v68, 4, v53
	v_ashrrev_i32_e32 v53, 31, v52
	v_lshlrev_b64 v[56:57], 10, v[54:55]
	v_lshlrev_b64 v[52:53], 10, v[52:53]
	v_lshl_add_u64 v[56:57], v[144:145], 0, v[56:57]
	v_mov_b32_e32 v69, v129
	v_lshl_add_u64 v[52:53], v[144:145], 0, v[52:53]
	v_lshl_add_u64 v[56:57], v[56:57], 0, v[68:69]
	v_lshl_add_u64 v[64:65], v[52:53], 0, v[68:69]
	global_load_dwordx4 v[48:51], v[48:49], off
	s_nop 0
	global_load_dwordx4 v[52:55], v[56:57], off offset:128
	s_nop 0
	global_load_dwordx4 v[56:59], v[56:57], off offset:192
	s_nop 0
	global_load_dwordx4 v[60:63], v[64:65], off offset:128
	s_nop 0
	global_load_dwordx4 v[64:67], v[64:65], off offset:192
	v_lshrrev_b32_e32 v70, 3, v101
	v_and_b32_e32 v70, 24, v70
	v_mul_u32_u24_e32 v70, 0x110, v70
	v_lshlrev_b32_e32 v71, 1, v155
	v_add3_u32 v159, s33, v70, v71
	v_mul_u32_u24_e32 v70, 0x88, v133
	v_lshlrev_b32_e32 v70, 1, v70
	v_lshlrev_b64 v[44:45], 1, v[44:45]
	v_lshlrev_b32_e32 v128, 2, v126
	v_add_u32_e32 v156, 0x8080, v127
	v_add3_u32 v160, s33, v70, v125
	v_or_b32_e32 v70, 32, v133
	v_or_b32_e32 v71, 64, v133
	v_lshl_add_u64 v[126:127], s[82:83], 0, v[44:45]
	v_lshl_add_u64 v[134:135], v[144:145], 0, v[44:45]
	v_lshlrev_b64 v[44:45], 1, v[46:47]
	v_mul_u32_u24_e32 v73, 0xd0, v70
	v_mul_u32_u24_e32 v74, 0xd0, v71
	v_lshlrev_b64 v[70:71], 1, v[118:119]
	v_lshl_add_u64 v[136:137], s[82:83], 0, v[44:45]
	v_lshl_add_u64 v[138:139], v[144:145], 0, v[44:45]
	v_sub_u32_e32 v44, 0x87f, v148
	v_lshl_add_u64 v[112:113], s[82:83], 0, v[70:71]
	v_lshl_add_u64 v[114:115], v[144:145], 0, v[70:71]
	v_lshlrev_b64 v[70:71], 1, v[120:121]
	v_lshrrev_b32_e32 v44, 8, v44
	v_mul_u32_u24_e32 v72, 0xd0, v133
	v_lshl_add_u64 v[118:119], s[82:83], 0, v[70:71]
	v_lshl_add_u64 v[120:121], v[144:145], 0, v[70:71]
	v_lshlrev_b64 v[70:71], 1, v[122:123]
	v_add_u32_e32 v45, 4, v44
	v_readlane_b32 s16, v253, 26
	v_mov_b32_e32 v80, 0
	v_add_u32_e32 v157, 0xffffff80, v124
	v_lshl_add_u32 v158, v102, 1, v106
	v_add_u32_e32 v161, 0x2200, v160
	v_add_u32_e32 v162, 0x4400, v160
	v_lshl_add_u64 v[122:123], s[82:83], 0, v[70:71]
	v_lshl_add_u64 v[124:125], v[144:145], 0, v[70:71]
	v_lshl_add_u64 v[140:141], v[102:103], 1, s[82:83]
	v_lshl_add_u64 v[142:143], v[102:103], 1, v[144:145]
	v_and_b32_e32 v163, 28, v45
	v_mov_b32_e32 v45, v44
	v_mov_b32_e32 v46, v44
	v_mov_b32_e32 v47, v44
	v_lshl_add_u64 v[144:145], v[144:145], 0, v[68:69]
	v_add_u32_e32 v164, s16, v105
	s_mov_b32 s53, 0
	v_add_u32_e32 v165, v107, v72
	v_add_u32_e32 v166, v107, v73
	v_add_u32_e32 v167, v107, v74
	v_mov_b32_e32 v81, v80
	v_mov_b32_e32 v82, v80
	v_mov_b32_e32 v83, v80
	v_mov_b32_e32 v76, v80
	v_mov_b32_e32 v77, v80
	v_mov_b32_e32 v78, v80
	v_mov_b32_e32 v79, v80
	v_mov_b32_e32 v72, v80
	v_mov_b32_e32 v73, v80
	v_mov_b32_e32 v74, v80
	v_mov_b32_e32 v75, v80
	v_mov_b32_e32 v68, v80
	v_mov_b32_e32 v69, v80
	v_mov_b32_e32 v70, v80
	v_mov_b32_e32 v71, v80
	v_mov_b32_e32 v96, v80
	v_mov_b32_e32 v97, v80
	v_mov_b32_e32 v98, v80
	v_mov_b32_e32 v99, v80
	v_mov_b32_e32 v92, v80
	v_mov_b32_e32 v93, v80
	v_mov_b32_e32 v94, v80
	v_mov_b32_e32 v95, v80
	v_mov_b32_e32 v88, v80
	v_mov_b32_e32 v89, v80
	v_mov_b32_e32 v90, v80
	v_mov_b32_e32 v91, v80
	v_mov_b32_e32 v84, v80
	v_mov_b32_e32 v85, v80
	v_mov_b32_e32 v86, v80
	v_mov_b32_e32 v87, v80
	v_mov_b32_e32 v104, v80
	v_mov_b32_e32 v105, v80
	v_mov_b32_e32 v106, v80
	v_mov_b32_e32 v107, v80
	v_mov_b32_e32 v100, v80
	v_mov_b32_e32 v101, v80
	v_mov_b32_e32 v102, v80
	v_mov_b32_e32 v103, v80
	v_readfirstlane_b32 s60, v131
	s_nop 0
	s_cmp_lt_u32 s60, 0x100
	s_cbranch_scc1 .Lmla_stg_pre
	s_barrier
.Lmla_stg_pre:
	s_branch .LBB0_1484

.LBB0_1504:
	v_readfirstlane_b32 s60, v131
	s_nop 0
	s_cmp_lt_u32 s60, 0x100
	s_cbranch_scc0 .Lmla_stg_post
	s_barrier
